# stacked + retention norm reductions: 6 ds_bpermute butterfly steps (xor 1/2/4) -> DPP adds (bitwise-identical sums)
# speedup vs baseline: 1.0011x; 1.0011x over previous
.LBB0_340:
	v_log_f32_e32 v85, v85
	v_add_u32_e32 v113, s11, v3
	v_add_u32_e32 v115, s33, v3
	s_mul_i32 s39, s40, 0x840
	v_sub_f32_e32 v111, v85, v84
	ds_read_b128 v[220:223], v113 offset:16384
	ds_read_b128 v[224:227], v115
	ds_read_b128 v[228:231], v115 offset:2048
	ds_read_b128 v[232:235], v113 offset:17408
	ds_read_b128 v[236:239], v115 offset:1024
	ds_read_b128 v[240:243], v115 offset:3072
	ds_read_b128 v[244:247], v113 offset:24576
	ds_read_b128 v[248:251], v115 offset:8192
	ds_read_b128 v[212:215], v115 offset:10240
	s_sub_i32 s39, s18, s39
	s_lshr_b32 s41, s40, 3
	s_mul_hi_u32 s40, s41, 0x840
	s_mulk_i32 s41, 0x840
	s_ashr_i32 s42, s39, 31
	s_add_u32 s60, s39, s41
	s_addc_u32 s61, s42, s40
	s_lshl_b32 s52, s23, 9
	s_mov_b64 s[40:41], 0x40000
	s_addk_i32 s22, 0x200
	s_add_i32 s19, s19, 8
	v_lshl_add_u64 v[108:109], v[108:109], 0, s[40:41]
	s_addk_i32 s18, 0x200
	s_waitcnt lgkmcnt(7)
	v_mfma_f32_16x16x32_bf16 v[88:91], v[220:223], v[224:227], 0
	s_waitcnt lgkmcnt(6)
	v_mfma_f32_16x16x32_bf16 v[84:87], v[220:223], v[228:231], 0
	ds_read_b128 v[220:223], v113 offset:25600
	ds_read_b128 v[224:227], v115 offset:9216
	ds_read_b128 v[228:231], v115 offset:11264
	v_add_u32_e32 v113, 0, v3
	v_add_u32_e32 v115, 0x10000, v113
	s_waitcnt lgkmcnt(7)
	v_mfma_f32_16x16x32_bf16 v[88:91], v[232:235], v[236:239], v[88:91]
	s_waitcnt lgkmcnt(6)
	v_mfma_f32_16x16x32_bf16 v[84:87], v[232:235], v[240:243], v[84:87]
	s_waitcnt lgkmcnt(4)
	v_mfma_f32_16x16x32_bf16 v[88:91], v[244:247], v[248:251], v[88:91]
	s_waitcnt lgkmcnt(3)
	v_mfma_f32_16x16x32_bf16 v[84:87], v[244:247], v[212:215], v[84:87]
	s_waitcnt lgkmcnt(1)
	v_mfma_f32_16x16x32_bf16 v[88:91], v[220:223], v[224:227], v[88:91]
	s_waitcnt lgkmcnt(0)
	v_mfma_f32_16x16x32_bf16 v[84:87], v[220:223], v[228:231], v[84:87]
	v_mul_f32_e32 v92, v128, v111
	v_mul_f32_e32 v93, v129, v111
	v_exp_f32_e32 v92, v92
	v_exp_f32_e32 v93, v93
	s_nop 1
	v_pk_mul_f32 v[88:89], v[92:93], v[88:89]
	v_mul_f32_e32 v92, v130, v111
	v_mul_f32_e32 v93, v131, v111
	v_exp_f32_e32 v92, v92
	v_exp_f32_e32 v93, v93
	v_cvt_pk_bf16_f32 v88, v88, v89
	v_pk_mul_f32 v[90:91], v[92:93], v[90:91]
	s_nop 0
	v_cvt_pk_bf16_f32 v89, v90, v91
	v_mul_f32_e32 v90, v132, v111
	v_mul_f32_e32 v91, v133, v111
	v_exp_f32_e32 v90, v90
	v_exp_f32_e32 v91, v91
	s_nop 0
	v_pk_mul_f32 v[84:85], v[90:91], v[84:85]
	v_mul_f32_e32 v90, v134, v111
	v_mul_f32_e32 v91, v135, v111
	v_exp_f32_e32 v90, v90
	v_exp_f32_e32 v91, v91
	v_cvt_pk_bf16_f32 v84, v84, v85
	v_pk_mul_f32 v[86:87], v[90:91], v[86:87]
	s_nop 0
	v_cvt_pk_bf16_f32 v85, v86, v87
	ds_write2st64_b64 v188, v[88:89], v[84:85] offset1:4
	v_add_u32_e32 v84, s38, v3
	s_waitcnt lgkmcnt(0)
	s_barrier
	ds_read_b128 v[96:99], v84 offset:49152
	ds_read_b128 v[116:119], v84 offset:50176
	ds_read_b128 v[220:223], v115
	ds_read_b128 v[224:227], v115 offset:2048
	ds_read_b128 v[228:231], v115 offset:4096
	ds_read_b128 v[232:235], v115 offset:6144
	ds_read_b128 v[236:239], v115 offset:1024
	ds_read_b128 v[240:243], v115 offset:3072
	ds_read_b128 v[244:247], v115 offset:5120
	ds_read_b128 v[248:251], v115 offset:7168
	ds_read_b128 v[212:215], v113
	s_waitcnt lgkmcnt(8)
	v_mfma_f32_16x16x32_bf16 v[84:87], v[220:223], v[96:99], 0
	ds_read_b128 v[220:223], v113 offset:2048
	s_waitcnt lgkmcnt(8)
	v_mfma_f32_16x16x32_bf16 v[88:91], v[224:227], v[96:99], 0
	ds_read_b128 v[224:227], v113 offset:4096
	s_waitcnt lgkmcnt(8)
	v_mfma_f32_16x16x32_bf16 v[92:95], v[228:231], v[96:99], 0
	ds_read_b128 v[228:231], v113 offset:6144
	s_waitcnt lgkmcnt(8)
	v_mfma_f32_16x16x32_bf16 v[96:99], v[232:235], v[96:99], 0
	ds_read_b128 v[232:235], v113 offset:1024
	s_waitcnt lgkmcnt(8)
	v_mfma_f32_16x16x32_bf16 v[84:87], v[236:239], v[116:119], v[84:87]
	ds_read_b128 v[236:239], v113 offset:3072
	s_waitcnt lgkmcnt(8)
	v_mfma_f32_16x16x32_bf16 v[88:91], v[240:243], v[116:119], v[88:91]
	ds_read_b128 v[240:243], v113 offset:5120
	s_waitcnt lgkmcnt(8)
	v_mfma_f32_16x16x32_bf16 v[92:95], v[244:247], v[116:119], v[92:95]
	ds_read_b128 v[244:247], v113 offset:7168
	s_waitcnt lgkmcnt(8)
	v_mfma_f32_16x16x32_bf16 v[96:99], v[248:251], v[116:119], v[96:99]
	ds_read_b128 v[248:251], v113 offset:8192
	s_waitcnt lgkmcnt(8)
	v_mfma_f32_16x16x32_bf16 v[116:119], v[212:215], v[80:83], 0
	ds_read_b128 v[212:215], v113 offset:10240
	s_waitcnt lgkmcnt(8)
	v_mfma_f32_16x16x32_bf16 v[190:193], v[220:223], v[80:83], 0
	ds_read_b128 v[220:223], v113 offset:12288
	s_waitcnt lgkmcnt(8)
	v_mfma_f32_16x16x32_bf16 v[208:211], v[224:227], v[80:83], 0
	ds_read_b128 v[224:227], v113 offset:14336
	s_waitcnt lgkmcnt(8)
	v_mfma_f32_16x16x32_bf16 v[80:83], v[228:231], v[80:83], 0
	ds_read_b128 v[228:231], v113 offset:9216
	s_waitcnt lgkmcnt(8)
	v_mfma_f32_16x16x32_bf16 v[116:119], v[232:235], v[76:79], v[116:119]
	ds_read_b128 v[232:235], v113 offset:11264
	s_waitcnt lgkmcnt(8)
	v_mfma_f32_16x16x32_bf16 v[190:193], v[236:239], v[76:79], v[190:193]
	ds_read_b128 v[236:239], v113 offset:13312
	s_waitcnt lgkmcnt(8)
	v_mfma_f32_16x16x32_bf16 v[208:211], v[240:243], v[76:79], v[208:211]
	ds_read_b128 v[240:243], v113 offset:15360
	s_waitcnt lgkmcnt(8)
	v_mfma_f32_16x16x32_bf16 v[76:79], v[244:247], v[76:79], v[80:83]
	s_waitcnt lgkmcnt(7)
	v_mfma_f32_16x16x32_bf16 v[80:83], v[248:251], v[72:75], v[116:119]
	s_waitcnt lgkmcnt(6)
	v_mfma_f32_16x16x32_bf16 v[116:119], v[212:215], v[72:75], v[190:193]
	s_waitcnt lgkmcnt(5)
	v_mfma_f32_16x16x32_bf16 v[190:193], v[220:223], v[72:75], v[208:211]
	s_waitcnt lgkmcnt(4)
	v_mfma_f32_16x16x32_bf16 v[72:75], v[224:227], v[72:75], v[76:79]
	s_waitcnt lgkmcnt(3)
	v_mfma_f32_16x16x32_bf16 v[76:79], v[228:231], v[68:71], v[80:83]
	s_waitcnt lgkmcnt(2)
	v_mfma_f32_16x16x32_bf16 v[80:83], v[232:235], v[68:71], v[116:119]
	s_waitcnt lgkmcnt(1)
	v_mfma_f32_16x16x32_bf16 v[116:119], v[236:239], v[68:71], v[190:193]
	s_waitcnt lgkmcnt(0)
	v_mfma_f32_16x16x32_bf16 v[68:71], v[240:243], v[68:71], v[72:75]
	s_nop 2
	v_mul_f32_e32 v72, v111, v136
	v_exp_f32_e32 v72, v72
	v_mul_f32_e32 v74, v111, v138
	v_mul_f32_e32 v75, v111, v139
	v_exp_f32_e32 v74, v74
	v_fma_f32 v72, v72, v76, v84
	v_mul_f32_e32 v76, v111, v141
	v_exp_f32_e32 v76, v76
	v_exp_f32_e32 v75, v75
	v_fma_f32 v74, v74, v78, v86
	v_mul_f32_e32 v78, v111, v143
	v_fma_f32 v76, v76, v81, v89
	v_mul_f32_e32 v81, v111, v147
	v_exp_f32_e32 v81, v81
	v_fmac_f32_e32 v87, v75, v79
	v_mul_f32_e32 v75, v111, v140
	v_mul_f32_e32 v73, v111, v137
	v_fmac_f32_e32 v95, v81, v119
	v_mul_f32_e32 v81, v111, v148
	v_exp_f32_e32 v81, v81
	v_exp_f32_e32 v75, v75
	v_exp_f32_e32 v78, v78
	v_exp_f32_e32 v73, v73
	v_fma_f32 v68, v81, v68, v96
	v_mul_f32_e32 v81, v111, v149
	v_exp_f32_e32 v81, v81
	v_fma_f32 v75, v75, v80, v88
	v_fmac_f32_e32 v91, v78, v83
	v_mul_f32_e32 v78, v111, v144
	v_fma_f32 v69, v81, v69, v97
	v_mul_f32_e32 v81, v111, v162
	v_exp_f32_e32 v81, v81
	v_mul_f32_e32 v79, v111, v145
	v_mul_f32_e32 v80, v111, v146
	v_fma_f32 v73, v73, v77, v85
	v_mul_f32_e32 v77, v111, v142
	v_exp_f32_e32 v78, v78
	v_exp_f32_e32 v79, v79
	v_exp_f32_e32 v80, v80
	v_fma_f32 v70, v81, v70, v98
	v_mul_f32_e32 v81, v111, v163
	v_exp_f32_e32 v77, v77
	v_exp_f32_e32 v81, v81
	v_fma_f32 v78, v78, v116, v92
	v_fma_f32 v79, v79, v117, v93
	v_fma_f32 v80, v80, v118, v94
	v_fma_f32 v77, v77, v82, v90
	v_fmac_f32_e32 v99, v81, v71
	ds_write_b32 v103, v72
	ds_write_b32 v164, v73
	ds_write_b32 v165, v74
	ds_write_b32 v166, v87
	ds_write_b32 v167, v75
	ds_write_b32 v168, v76
	ds_write_b32 v169, v77
	ds_write_b32 v170, v91
	ds_write_b32 v171, v78
	ds_write_b32 v172, v79
	ds_write_b32 v173, v80
	ds_write_b32 v174, v95
	ds_write_b32 v127, v68
	ds_write_b32 v175, v69
	ds_write_b32 v176, v70
	ds_write_b32 v177, v99
	s_waitcnt lgkmcnt(0)
	s_barrier
	ds_read_b128 v[82:85], v120
	ds_read_b128 v[78:81], v121
	ds_read_b128 v[72:75], v122
	ds_read_b128 v[68:71], v123
	v_lshl_add_u64 v[90:91], v[106:107], 0, s[52:53]
	v_lshlrev_b32_e32 v190, 16, v64
	s_waitcnt lgkmcnt(2)
	v_pk_add_f32 v[86:87], v[82:83], v[78:79]
	v_pk_add_f32 v[76:77], v[84:85], v[80:81]
	s_waitcnt lgkmcnt(1)
	v_pk_add_f32 v[86:87], v[86:87], v[72:73]
	v_pk_add_f32 v[76:77], v[76:77], v[74:75]
	s_waitcnt lgkmcnt(0)
	v_pk_add_f32 v[86:87], v[86:87], v[68:69]
	v_pk_add_f32 v[76:77], v[76:77], v[70:71]
	v_add_f32_e32 v86, v86, v87
	v_add_f32_e32 v76, v76, v86
	v_add_f32_e32 v76, v77, v76
	v_and_b32_e32 v191, 0xffff0000, v64
	v_mul_f32_e32 v64, 0xbfb8aa3b, v190
	v_exp_f32_e32 v64, v64
	v_lshl_add_u64 v[94:95], s[60:61], 0, v[100:101]
	v_add_f32_dpp v76, v76, v76 quad_perm:[1,0,3,2] row_mask:0xf bank_mask:0xf
	v_add_f32_e32 v64, 1.0, v64
	v_rcp_f32_e32 v192, v64
	v_mul_f32_e32 v64, 0xbfb8aa3b, v191
	v_exp_f32_e32 v64, v64
	v_add_f32_dpp v76, v76, v76 quad_perm:[2,3,0,1] row_mask:0xf bank_mask:0xf
	s_lshl_b32 s52, s23, 8
	v_add_f32_e32 v64, 1.0, v64
	v_rcp_f32_e32 v193, v64
	v_add_f32_dpp v76, v76, v76 row_half_mirror row_mask:0xf bank_mask:0xf
	v_fmamk_f32 v79, v76, 0xbc000000, v79
	v_fmac_f32_e32 v78, 0xbc000000, v76
	v_fmamk_f32 v119, v76, 0xbc000000, v83
	v_fmamk_f32 v118, v76, 0xbc000000, v82
	v_fmamk_f32 v117, v76, 0xbc000000, v81
	v_fmamk_f32 v116, v76, 0xbc000000, v80
	v_fmamk_f32 v97, v76, 0xbc000000, v69
	v_fmamk_f32 v96, v76, 0xbc000000, v68
	v_pk_mul_f32 v[68:69], v[78:79], v[78:79]
	v_fmamk_f32 v85, v76, 0xbc000000, v85
	v_fmac_f32_e32 v84, 0xbc000000, v76
	v_fmamk_f32 v99, v76, 0xbc000000, v75
	v_fmamk_f32 v98, v76, 0xbc000000, v74
	v_fmamk_f32 v73, v76, 0xbc000000, v73
	v_fmac_f32_e32 v72, 0xbc000000, v76
	v_pk_mul_f32 v[74:75], v[116:117], v[116:117]
	v_pk_fma_f32 v[68:69], v[118:119], v[118:119], v[68:69]
	v_pk_fma_f32 v[74:75], v[84:85], v[84:85], v[74:75]
	v_pk_fma_f32 v[68:69], v[72:73], v[72:73], v[68:69]
	v_fmamk_f32 v71, v76, 0xbc000000, v71
	v_fmac_f32_e32 v70, 0xbc000000, v76
	v_pk_fma_f32 v[74:75], v[98:99], v[98:99], v[74:75]
	v_pk_fma_f32 v[68:69], v[96:97], v[96:97], v[68:69]
	v_pk_fma_f32 v[74:75], v[70:71], v[70:71], v[74:75]
	v_add_f32_e32 v68, v68, v69
	v_add_f32_e32 v68, v74, v68
	v_add_f32_e32 v68, v75, v68
	global_load_dwordx4 v[74:77], v[90:91], off offset:48
	global_load_dwordx4 v[80:83], v[90:91], off offset:32
	global_load_dwordx4 v[86:89], v[90:91], off offset:16
	s_nop 0
	global_load_dwordx4 v[90:93], v[90:91], off
	s_nop 1
	v_add_f32_dpp v68, v68, v68 quad_perm:[1,0,3,2] row_mask:0xf bank_mask:0xf
	s_nop 1
	v_add_f32_dpp v68, v68, v68 quad_perm:[2,3,0,1] row_mask:0xf bank_mask:0xf
	s_nop 1
	v_add_f32_dpp v68, v68, v68 row_half_mirror row_mask:0xf bank_mask:0xf
	v_fmamk_f32 v68, v68, 0x3c000000, v180
	v_cmp_gt_f32_e32 vcc, s7, v68
	v_mul_f32_e32 v69, 0x4b800000, v68
	s_nop 0
	v_cndmask_b32_e32 v68, v68, v69, vcc
	v_rsq_f32_e32 v68, v68
	s_nop 0
	v_mul_f32_e32 v69, 0x45800000, v68
	v_cndmask_b32_e32 v68, v68, v69, vcc
	v_pk_mul_f32 v[118:119], v[118:119], v[68:69] op_sel_hi:[1,0]
	v_pk_mul_f32 v[84:85], v[84:85], v[68:69] op_sel_hi:[1,0]
	v_pk_mul_f32 v[78:79], v[78:79], v[68:69] op_sel_hi:[1,0]
	v_pk_mul_f32 v[72:73], v[72:73], v[68:69] op_sel_hi:[1,0]
	s_andn2_b64 vcc, exec, s[36:37]
	s_waitcnt vmcnt(2)
	v_pk_mul_f32 v[72:73], v[80:81], v[72:73]
	s_waitcnt vmcnt(1)
	v_pk_mul_f32 v[78:79], v[86:87], v[78:79]
	s_waitcnt vmcnt(0)
	v_pk_mul_f32 v[90:91], v[90:91], v[118:119]
	v_pk_mul_f32 v[118:119], v[192:193], v[190:191]
	v_pk_mul_f32 v[84:85], v[92:93], v[84:85]
	v_pk_mul_f32 v[90:91], v[118:119], v[90:91]
	v_pk_mul_f32 v[86:87], v[116:117], v[68:69] op_sel_hi:[1,0]
	v_cvt_pk_bf16_f32 v64, v90, v91
	v_lshlrev_b32_e32 v90, 16, v65
	v_and_b32_e32 v91, 0xffff0000, v65
	v_mul_f32_e32 v65, 0xbfb8aa3b, v90
	v_exp_f32_e32 v65, v65
	v_pk_mul_f32 v[86:87], v[88:89], v[86:87]
	v_pk_mul_f32 v[80:81], v[98:99], v[68:69] op_sel_hi:[1,0]
	v_add_f32_e32 v65, 1.0, v65
	v_rcp_f32_e32 v118, v65
	v_mul_f32_e32 v65, 0xbfb8aa3b, v91
	v_exp_f32_e32 v65, v65
	v_pk_mul_f32 v[80:81], v[82:83], v[80:81]
	v_add_f32_e32 v65, 1.0, v65
	v_rcp_f32_e32 v119, v65
	s_nop 0
	v_pk_mul_f32 v[90:91], v[118:119], v[90:91]
	s_nop 0
	v_pk_mul_f32 v[84:85], v[90:91], v[84:85]
	s_nop 0
	v_cvt_pk_bf16_f32 v65, v84, v85
	v_lshlrev_b32_e32 v84, 16, v66
	v_and_b32_e32 v85, 0xffff0000, v66
	v_mul_f32_e32 v66, 0xbfb8aa3b, v84
	v_exp_f32_e32 v66, v66
	s_nop 0
	v_add_f32_e32 v66, 1.0, v66
	v_rcp_f32_e32 v90, v66
	v_mul_f32_e32 v66, 0xbfb8aa3b, v85
	v_exp_f32_e32 v66, v66
	s_nop 0
	v_add_f32_e32 v66, 1.0, v66
	v_rcp_f32_e32 v91, v66
	s_nop 0
	v_pk_mul_f32 v[84:85], v[90:91], v[84:85]
	s_nop 0
	v_pk_mul_f32 v[78:79], v[84:85], v[78:79]
	s_nop 0
	v_cvt_pk_bf16_f32 v66, v78, v79
	v_lshlrev_b32_e32 v78, 16, v67
	v_and_b32_e32 v79, 0xffff0000, v67
	v_mul_f32_e32 v67, 0xbfb8aa3b, v78
	v_exp_f32_e32 v67, v67
	s_nop 0
	v_add_f32_e32 v67, 1.0, v67
	v_rcp_f32_e32 v84, v67
	v_mul_f32_e32 v67, 0xbfb8aa3b, v79
	v_exp_f32_e32 v67, v67
	s_nop 0
	v_add_f32_e32 v67, 1.0, v67
	v_rcp_f32_e32 v85, v67
	s_nop 0
	v_pk_mul_f32 v[78:79], v[84:85], v[78:79]
	s_nop 0
	v_pk_mul_f32 v[78:79], v[78:79], v[86:87]
	s_nop 0
	v_cvt_pk_bf16_f32 v67, v78, v79
	v_lshlrev_b32_e32 v78, 16, v36
	v_and_b32_e32 v79, 0xffff0000, v36
	v_mul_f32_e32 v36, 0xbfb8aa3b, v78
	v_exp_f32_e32 v36, v36
	s_nop 0
	v_add_f32_e32 v36, 1.0, v36
	v_rcp_f32_e32 v84, v36
	v_mul_f32_e32 v36, 0xbfb8aa3b, v79
	v_exp_f32_e32 v36, v36
	s_nop 0
	v_add_f32_e32 v36, 1.0, v36
	v_rcp_f32_e32 v85, v36
	s_nop 0
	v_pk_mul_f32 v[78:79], v[84:85], v[78:79]
	s_nop 0
	v_pk_mul_f32 v[72:73], v[78:79], v[72:73]
	s_nop 0
	v_cvt_pk_bf16_f32 v36, v72, v73
	v_lshlrev_b32_e32 v72, 16, v37
	v_and_b32_e32 v73, 0xffff0000, v37
	v_mul_f32_e32 v37, 0xbfb8aa3b, v72
	v_exp_f32_e32 v37, v37
	s_nop 0
	v_add_f32_e32 v37, 1.0, v37
	v_rcp_f32_e32 v78, v37
	v_mul_f32_e32 v37, 0xbfb8aa3b, v73
	v_exp_f32_e32 v37, v37
	s_nop 0
	v_add_f32_e32 v37, 1.0, v37
	v_rcp_f32_e32 v79, v37
	s_nop 0
	v_pk_mul_f32 v[72:73], v[78:79], v[72:73]
	s_nop 0
	v_pk_mul_f32 v[72:73], v[72:73], v[80:81]
	v_pk_mul_f32 v[80:81], v[96:97], v[68:69] op_sel_hi:[1,0]
	v_cvt_pk_bf16_f32 v37, v72, v73
	v_lshlrev_b32_e32 v72, 16, v38
	v_and_b32_e32 v73, 0xffff0000, v38
	v_mul_f32_e32 v38, 0xbfb8aa3b, v72
	v_exp_f32_e32 v38, v38
	v_pk_mul_f32 v[74:75], v[74:75], v[80:81]
	v_pk_mul_f32 v[68:69], v[70:71], v[68:69] op_sel_hi:[1,0]
	v_mov_b64_e32 v[82:83], v[54:55]
	v_add_f32_e32 v38, 1.0, v38
	v_rcp_f32_e32 v78, v38
	v_mul_f32_e32 v38, 0xbfb8aa3b, v73
	v_exp_f32_e32 v38, v38
	v_pk_mul_f32 v[68:69], v[76:77], v[68:69]
	v_mov_b64_e32 v[80:81], v[52:53]
	v_add_f32_e32 v38, 1.0, v38
	v_rcp_f32_e32 v79, v38
	s_nop 0
	v_pk_mul_f32 v[72:73], v[78:79], v[72:73]
	s_nop 0
	v_pk_mul_f32 v[72:73], v[72:73], v[74:75]
	v_mov_b64_e32 v[78:79], v[50:51]
	v_cvt_pk_bf16_f32 v38, v72, v73
	v_lshlrev_b32_e32 v72, 16, v39
	v_and_b32_e32 v73, 0xffff0000, v39
	v_mul_f32_e32 v39, 0xbfb8aa3b, v72
	v_exp_f32_e32 v39, v39
	v_mov_b64_e32 v[76:77], v[48:49]
	v_add_f32_e32 v39, 1.0, v39
	v_rcp_f32_e32 v74, v39
	v_mul_f32_e32 v39, 0xbfb8aa3b, v73
	v_exp_f32_e32 v39, v39
	s_nop 0
	v_add_f32_e32 v39, 1.0, v39
	v_rcp_f32_e32 v75, v39
	s_nop 0
	v_pk_mul_f32 v[70:71], v[74:75], v[72:73]
	s_nop 0
	v_pk_mul_f32 v[68:69], v[70:71], v[68:69]
	v_mov_b64_e32 v[74:75], v[46:47]
	v_cvt_pk_bf16_f32 v39, v68, v69
	v_lshlrev_b64 v[68:69], 12, v[94:95]
	v_lshl_add_u64 v[68:69], v[4:5], 0, v[68:69]
	v_lshl_add_u64 v[68:69], v[68:69], 0, s[52:53]
	v_lshl_add_u64 v[68:69], v[68:69], 0, v[0:1]
	global_store_dwordx4 v[68:69], v[64:67], off
	global_store_dwordx4 v[68:69], v[36:39], off offset:16
	v_mov_b64_e32 v[70:71], v[42:43]
	v_mov_b64_e32 v[66:67], v[62:63]
	v_mov_b64_e32 v[36:37], v[56:57]
	v_mov_b64_e32 v[72:73], v[44:45]
	v_mov_b64_e32 v[68:69], v[40:41]
	v_mov_b64_e32 v[64:65], v[60:61]
	v_mov_b64_e32 v[38:39], v[58:59]
	s_cbranch_vccz .LBB0_343
